# P5 Y2: mask-pointer bump moved into the permlane wait slot (replaces s_nop) on top of the combined trims
# baseline (speedup 1.0000x reference)
; __device__ __forceinline__ void sel_mask_tile(f32x16& p0, f32x16& p1, unsigned wlo, unsigned whi, int hi) {
;     const unsigned NEGB = 0xff800000u;
;     const unsigned lo = wlo >> (4 * hi), h2 = whi >> (4 * hi);
; #pragma unroll
;     for (int r = 0; r < 16; ++r) {
;         const int c = (r & 3) + 8 * (r >> 2);
;         const unsigned m0 = (unsigned)__builtin_amdgcn_sbfe((int)lo, c, 1), m1 = (unsigned)__builtin_amdgcn_sbfe((int)h2, c, 1);
;         p0[r] = __uint_as_float((__float_as_uint(p0[r]) & m0) | (NEGB & ~m0));
;         p1[r] = __uint_as_float((__float_as_uint(p1[r]) & m1) | (NEGB & ~m1));
;     }
; }
; __device__ __forceinline__ void partialSM(f32x16& p0, f32x16& p1, float& m_reg, float& mn, float& alpha) {
;     float pmax = p0[0];
; #pragma unroll
;     for (int r = 1; r < 16; ++r) pmax = fmaxf(pmax, p0[r]);
; #pragma unroll
;     for (int r = 0; r < 16; ++r) pmax = fmaxf(pmax, p1[r]);
;     { auto rr = __builtin_amdgcn_permlane32_swap(__float_as_uint(pmax), __float_as_uint(pmax), false, false);
;       pmax = fmaxf(__uint_as_float(rr[0]), __uint_as_float(rr[1])); }
;     constexpr float C2 = 1.4426950408889634f * SCALE;
;     if (__builtin_expect(__all((pmax - m_reg) * SCALE <= THR), 1)) { mn = m_reg; alpha = 1.f; }
;     else { mn = fmaxf(m_reg, pmax); alpha = __builtin_amdgcn_exp2f((m_reg - mn) * C2); m_reg = mn; }
.Lp5_k1_skip:
	s_waitcnt lgkmcnt(0)
	s_barrier
	v_lshrrev_b32_e32 v193, v163, v228
	v_bfe_i32 v192, v193, 0, 1
	v_bitop3_b32 v192, v82, s74, v192 bitop3:0xe4
	v_bfe_i32 v82, v193, 1, 1
	v_bitop3_b32 v146, v83, s74, v82 bitop3:0xe4
	v_bfe_i32 v82, v193, 2, 1
	v_bitop3_b32 v147, v84, s74, v82 bitop3:0xe4
	v_bfe_i32 v82, v193, 3, 1
	v_bitop3_b32 v148, v85, s74, v82 bitop3:0xe4
	v_bfe_i32 v82, v193, 8, 1
	v_bitop3_b32 v149, v86, s74, v82 bitop3:0xe4
	v_bfe_i32 v82, v193, 9, 1
	v_bitop3_b32 v150, v87, s74, v82 bitop3:0xe4
	v_bfe_i32 v82, v193, 10, 1
	v_bitop3_b32 v88, v88, s74, v82 bitop3:0xe4
	v_bfe_i32 v82, v193, 11, 1
	v_bitop3_b32 v89, v89, s74, v82 bitop3:0xe4
	v_bfe_i32 v82, v193, 16, 1
	v_bitop3_b32 v90, v90, s74, v82 bitop3:0xe4
	v_bfe_i32 v82, v193, 17, 1
	v_bitop3_b32 v91, v91, s74, v82 bitop3:0xe4
	v_bfe_i32 v82, v193, 18, 1
	v_bitop3_b32 v92, v92, s74, v82 bitop3:0xe4
	v_bfe_i32 v82, v193, 19, 1
	v_bitop3_b32 v93, v93, s74, v82 bitop3:0xe4
	v_bfe_i32 v82, v193, 24, 1
	v_bitop3_b32 v94, v94, s74, v82 bitop3:0xe4
	v_bfe_i32 v82, v193, 25, 1
	v_bitop3_b32 v95, v95, s74, v82 bitop3:0xe4
	v_bfe_i32 v82, v193, 26, 1
	v_bitop3_b32 v96, v96, s74, v82 bitop3:0xe4
	v_bfe_i32 v82, v193, 27, 1
	v_bitop3_b32 v97, v97, s74, v82 bitop3:0xe4
	v_max_f32_e32 v82, v192, v146
	v_max3_f32 v82, v82, v147, v148
	v_max3_f32 v82, v82, v149, v150
	v_max3_f32 v82, v82, v88, v89
	v_max3_f32 v82, v82, v90, v91
	v_lshrrev_b32_e32 v194, v163, v229
	v_max3_f32 v82, v82, v92, v93
	v_bfe_i32 v195, v194, 0, 1
	v_bfe_i32 v172, v194, 1, 1
	v_max3_f32 v82, v82, v94, v95
	v_bitop3_b32 v66, v66, s74, v195 bitop3:0xe4
	v_bfe_i32 v83, v194, 2, 1
	v_bfe_i32 v84, v194, 3, 1
	v_max3_f32 v230, v82, v96, v97
	v_bitop3_b32 v67, v67, s74, v172 bitop3:0xe4
	v_bfe_i32 v85, v194, 8, 1
	v_bfe_i32 v86, v194, 9, 1
	v_bitop3_b32 v82, v68, s74, v83 bitop3:0xe4
	v_max3_f32 v68, v230, v66, v67
	v_bitop3_b32 v83, v69, s74, v84 bitop3:0xe4
	v_bfe_i32 v87, v194, 10, 1
	v_bfe_i32 v151, v194, 11, 1
	v_bitop3_b32 v84, v70, s74, v85 bitop3:0xe4
	v_max3_f32 v68, v68, v82, v83
	v_bitop3_b32 v85, v71, s74, v86 bitop3:0xe4
	v_bfe_i32 v152, v194, 16, 1
	v_bfe_i32 v153, v194, 17, 1
	v_bitop3_b32 v86, v72, s74, v87 bitop3:0xe4
	v_max3_f32 v68, v68, v84, v85
	v_bitop3_b32 v87, v73, s74, v151 bitop3:0xe4
	v_bfe_i32 v154, v194, 18, 1
	v_bfe_i32 v155, v194, 19, 1
	v_bitop3_b32 v74, v74, s74, v152 bitop3:0xe4
	v_max3_f32 v69, v68, v86, v87
	v_bitop3_b32 v75, v75, s74, v153 bitop3:0xe4
	v_bfe_i32 v156, v194, 24, 1
	v_bfe_i32 v157, v194, 25, 1
	v_bitop3_b32 v68, v76, s74, v154 bitop3:0xe4
	v_max3_f32 v71, v69, v74, v75
	v_bitop3_b32 v69, v77, s74, v155 bitop3:0xe4
	v_bfe_i32 v230, v194, 26, 1
	v_bfe_i32 v231, v194, 27, 1
	v_bitop3_b32 v70, v78, s74, v156 bitop3:0xe4
	v_max3_f32 v73, v71, v68, v69
	v_bitop3_b32 v71, v79, s74, v157 bitop3:0xe4
	v_bitop3_b32 v72, v80, s74, v230 bitop3:0xe4
	v_max3_f32 v76, v73, v70, v71
	v_bitop3_b32 v73, v81, s74, v231 bitop3:0xe4
	v_max3_f32 v76, v76, v72, v73
	v_mov_b32_e32 v77, v76
	v_mov_b32_e32 v207, 1.0
	v_add_u32_e32 v179, 16, v179
	v_permlane32_swap_b32_e32 v76, v77
	v_max_f32_e32 v76, v76, v77
	v_fmamk_f32 v77, v76, 0x3e0293ee, v190
	v_cmp_ge_f32_e32 vcc, 0x4138aa3b, v77
	s_cmp_eq_u64 vcc, exec
	s_cselect_b64 s[6:7], -1, 0

; __device__ __forceinline__ void partialSM(f32x16& p0, f32x16& p1, float& m_reg, float& mn, float& alpha) {
;     ...
;     const float mnL = -mn * C2;
; #pragma unroll
;     for (int r = 0; r < 16; ++r) p0[r] = fmaf(p0[r], C2, mnL);
; #pragma unroll
;     for (int r = 0; r < 16; ++r) p1[r] = fmaf(p1[r], C2, mnL);
; #pragma unroll
;     for (int r = 0; r < 16; ++r) p0[r] = __builtin_amdgcn_exp2f(p0[r]);
; __device__ __forceinline__ void finishSM(f32x16& p0, f32x16& p1, float alpha, float& l_reg, bf16x8& pa0, bf16x8& pa1, bf16x8& pa2, bf16x8& pa3) {
;     ...
;     l_reg = l_reg * alpha + ps;
.LBB0_1311:
	v_fmamk_f32 v77, v192, 0x3e0293ee, v190
	v_fmamk_f32 v78, v146, 0x3e0293ee, v190
	v_fmamk_f32 v79, v147, 0x3e0293ee, v190
	v_fmamk_f32 v80, v148, 0x3e0293ee, v190
	v_fmamk_f32 v81, v149, 0x3e0293ee, v190
	v_fmamk_f32 v250, v150, 0x3e0293ee, v190
	v_fmamk_f32 v88, v88, 0x3e0293ee, v190
	v_fmamk_f32 v89, v89, 0x3e0293ee, v190
	v_fmamk_f32 v90, v90, 0x3e0293ee, v190
	v_fmamk_f32 v91, v91, 0x3e0293ee, v190
	v_fmamk_f32 v92, v92, 0x3e0293ee, v190
	v_fmamk_f32 v93, v93, 0x3e0293ee, v190
	v_fmamk_f32 v94, v94, 0x3e0293ee, v190
	v_fmamk_f32 v95, v95, 0x3e0293ee, v190
	v_fmamk_f32 v96, v96, 0x3e0293ee, v190
	v_fmamk_f32 v251, v97, 0x3e0293ee, v190
	v_exp_f32_e32 v219, v77
	v_exp_f32_e32 v220, v78
	v_exp_f32_e32 v221, v79
	v_exp_f32_e32 v222, v80
	v_exp_f32_e32 v223, v81
	v_exp_f32_e32 v225, v250
	v_exp_f32_e32 v224, v88
	v_exp_f32_e32 v226, v89
	v_exp_f32_e32 v211, v90
	v_exp_f32_e32 v212, v91
	v_exp_f32_e32 v213, v92
	v_exp_f32_e32 v215, v93
	v_exp_f32_e32 v214, v94
	v_exp_f32_e32 v216, v95
	v_exp_f32_e32 v217, v96
	v_exp_f32_e32 v218, v251
	v_fmamk_f32 v194, v66, 0x3e0293ee, v190
	v_fmamk_f32 v195, v67, 0x3e0293ee, v190
	v_fmac_f32_e32 v181, v177, v205
	v_fmamk_f32 v192, v82, 0x3e0293ee, v190
	v_fmamk_f32 v193, v83, 0x3e0293ee, v190
	v_fmamk_f32 v158, v84, 0x3e0293ee, v190
	v_fmamk_f32 v159, v85, 0x3e0293ee, v190
	v_fmamk_f32 v154, v86, 0x3e0293ee, v190
	v_fmamk_f32 v155, v87, 0x3e0293ee, v190
	v_fmamk_f32 v150, v74, 0x3e0293ee, v190
	v_fmamk_f32 v151, v75, 0x3e0293ee, v190
	v_fmamk_f32 v160, v68, 0x3e0293ee, v190
	v_fmamk_f32 v161, v69, 0x3e0293ee, v190
	v_fmamk_f32 v156, v70, 0x3e0293ee, v190
	v_fmamk_f32 v157, v71, 0x3e0293ee, v190
	v_fmamk_f32 v152, v72, 0x3e0293ee, v190
	v_fmamk_f32 v153, v73, 0x3e0293ee, v190
	v_fma_f32 v205, v181, v208, v209
	s_add_u32 s16, s16, 0x40000
	s_addc_u32 s17, s17, 0
	s_add_u32 s100, s100, 0x40000
	s_addc_u32 s101, s101, 0
	s_cmp_ge_u32 s82, s81
	s_cbranch_scc1 .Lp5_exit
	v_mov_b32_e32 v177, v207
	s_branch .LBB0_1299
